# speedup vs baseline: 1.0078x; 1.0044x over previous
; #define PG8_STAGE(bufoff, gbase, voff) do { _Pragma("unroll") for (int _i = 0; _i < 2; ++_i) \
;         __builtin_amdgcn_global_load_lds((const unsigned*)((const char*)(gbase) + (voff)[_i]), (PG8_LAS unsigned*)(lds + (bufoff) + ldsw + _i * 8192), 16, 0, 0); } while (0)
; #define PG8_WAIT_V(n) asm volatile("s_waitcnt vmcnt(" #n ")" ::: "memory")
; #define PG8_BAR __builtin_amdgcn_s_barrier()
; template <class Epi, class Sched, bool ALIGN_EPI = false, bool SP2 = false>
; __device__ __forceinline__ void gemm_phase(PG8_LAS unsigned char* lds, const Gemm g, const Sched& S, const Epi& E) {
;     ...
;     const char* cA = (const char*)g.A + (size_t)cur.pm * tstep; const char* cB = (const char*)g.Bt + (size_t)cur.pn * tstep;
;     S.a_ready(cur);
;     if constexpr (SP2) {
;         PG8_STAGE(PG8_SB(0, 0), cB, voffB); PG8_STAGE(PG8_SB(0, 1), cB + hstep, voffB); PG8_STAGE(PG8_SA(0, 0), cA, voffA); PG8_STAGE(PG8_SA(0, 1), cA + hstep, voffA);
;         if (wr == 1) PG8_BAR;
;         PG8_WAIT_V(2); PG8_BAR;
;         PG8_STAGE(PG8_SB(1, 0), cB + kstep, voffB); PG8_STAGE(PG8_SA(1, 0), cA + kstep, voffA); PG8_STAGE(PG8_SB(1, 1), cB + hstep + kstep, voffB);
;         PG8_WAIT_V(6); PG8_BAR;
.LBB0_162:
	v_and_b32_e32 v15, 15, v14
	v_lshrrev_b32_e32 v14, 1, v14
	v_and_b32_e32 v14, 24, v14
	v_lshlrev_b32_e32 v16, 1, v14
	s_add_u32 s61, s12, 0x13200000
	v_lshl_or_b32 v140, s6, 6, v15
	v_lshl_or_b32 v16, v15, 6, v16
	v_lshlrev_b32_e32 v15, 2, v15
	s_addc_u32 s97, s13, 0
	s_lshl_b32 s7, s6, 13
	v_and_b32_e32 v17, 32, v15
	s_lshl_b32 s4, s4, 5
	v_bitop3_b32 v18, v16, s7, v17 bitop3:0xde
	s_and_b32 s7, s4, 0x60
	s_lshl_b32 s4, s7, 7
	s_add_i32 m0, s85, 0x18000
	v_lshl_add_u64 v[6:7], v[6:7], 0, s[92:93]
	v_bitop3_b32 v141, v16, s4, v17 bitop3:0xde
	s_waitcnt vmcnt(2)
	s_barrier
	global_load_lds_dwordx4 v[6:7], off
	v_lshl_add_u64 v[4:5], v[4:5], 0, s[92:93]
	s_add_i32 m0, s85, 0x1a000
	s_add_i32 s50, s85, 0x8000
	s_add_i32 s4, s85, 0xa000
	global_load_lds_dwordx4 v[4:5], off
	v_lshl_add_u64 v[0:1], v[0:1], 0, s[92:93]
	s_mov_b32 m0, s50
	s_add_u32 s26, s38, 0x40080
	global_load_lds_dwordx4 v[0:1], off
	v_lshl_add_u64 v[0:1], v[2:3], 0, s[92:93]
	s_mov_b32 m0, s4
	s_addc_u32 s27, s39, 0
	global_load_lds_dwordx4 v[0:1], off
	s_add_i32 m0, s85, 0x1c000
	v_lshl_add_u64 v[0:1], s[26:27], 0, v[220:221]
	global_load_lds_dwordx4 v[0:1], off
	v_lshl_add_u64 v[0:1], s[26:27], 0, v[128:129]
	s_add_i32 m0, s85, 0x1e000
	s_cmpk_lt_u32 s5, 0x100
	global_load_lds_dwordx4 v[0:1], off
	v_lshlrev_b32_e32 v0, 14, v8
	v_and_b32_e32 v0, 0xffff8000, v0
	v_lshl_add_u32 v0, v9, 11, v0
	v_and_b32_e32 v1, 1, v8
	v_lshl_or_b32 v0, v1, 6, v0
	v_lshl_add_u32 v134, v10, 1, v0
	v_lshlrev_b32_e32 v0, 14, v12
	s_cselect_b64 s[26:27], -1, 0
	s_lshl_b32 s5, s6, 8
	v_and_b32_e32 v0, 0xffff8000, v0
	s_waitcnt vmcnt(6)
	s_add_i32 s5, s5, 0
	v_lshl_add_u32 v0, v11, 11, v0
	v_and_b32_e32 v1, 1, v12
	s_add_i32 s5, s5, 0x20400
	v_lshl_or_b32 v0, v1, 6, v0
	v_readlane_b32 s0, v255, 30
	v_add_u32_e32 v142, s5, v15
	v_or_b32_e32 v143, s7, v14
	v_mov_b32_e32 v135, v221
	v_lshl_add_u32 v136, v13, 1, v0
	v_mov_b32_e32 v137, v221
	s_mov_b32 s57, 0
	v_add_u32_e32 v144, 0, v18
	v_readlane_b32 s40, v255, 29
	s_mov_b32 s41, s0
	s_mov_b32 s5, 0
	s_barrier
	v_readlane_b32 s1, v255, 31
	s_cmp_eq_u32 s98, 0
	s_cbranch_scc1 .Lmy_g_noprio
	s_setprio 1
.Lmy_g_noprio:
	s_branch .LBB0_165
.LBB0_163:
	s_mov_b64 s[38:39], 0

; #define PG8_STAGE(bufoff, gbase, voff) do { _Pragma("unroll") for (int _i = 0; _i < 2; ++_i) \
;         __builtin_amdgcn_global_load_lds((const unsigned*)((const char*)(gbase) + (voff)[_i]), (PG8_LAS unsigned*)(lds + (bufoff) + ldsw + _i * 8192), 16, 0, 0); } while (0)
; #define PG8_LDA(dst, b, h) do { _Pragma("unroll") for (int m = 0; m < 4; ++m) _Pragma("unroll") for (int k = 0; k < 2; ++k) dst[m][k] = *(const PG8_LAS bf16x8*)(lds + PG8_SA(b, h) + aoff + m * 2048 + k * 1024); } while (0)
; #define PG8_LDB(dst, b, h) do { _Pragma("unroll") for (int n = 0; n < 2; ++n) _Pragma("unroll") for (int k = 0; k < 2; ++k) dst[n][k] = *(const PG8_LAS bf16x8*)(lds + PG8_SB(b, h) + boff + n * 2048 + k * 1024); } while (0)
; #define PG8_MMA(ai, bj, At, Bt) do { __builtin_amdgcn_s_setprio(1); _Pragma("unroll") for (int m = 0; m < 4; ++m) _Pragma("unroll") for (int n = 0; n < 2; ++n) _Pragma("unroll") for (int k = 0; k < 2; ++k) \
;         acc[ai][bj][m][n] = __builtin_amdgcn_mfma_f32_16x16x32_bf16(Bt[n][k], At[m][k], acc[ai][bj][m][n], 0, 0, 0); __builtin_amdgcn_s_setprio(0); } while (0)
; #define PG8_WAIT_V(n) asm volatile("s_waitcnt vmcnt(" #n ")" ::: "memory")
; #define PG8_WAIT_L(n) asm volatile("s_waitcnt lgkmcnt(" #n ")" ::: "memory")
; #define PG8_BAR __builtin_amdgcn_s_barrier()
; #define PG8_SCHED __builtin_amdgcn_sched_barrier(0)
; template <class Epi, class Sched, bool ALIGN_EPI = false, bool SP2 = false>
; __device__ __forceinline__ void gemm_phase(PG8_LAS unsigned char* lds, const Gemm g, const Sched& S, const Epi& E) {
;     ...
;             PG8_LDB(B0, 0, 0); PG8_LDB(B1, 0, 1); PG8_SCHED; PG8_LDA(At, 0, 0); PG8_STAGE(PG8_SA(1, 1), a1 + hstep, voffA);
;             PG8_WAIT_V(8); PG8_WAIT_L(0); PG8_BAR; PG8_MMA(0, 0, At, B0); PG8_MMA(0, 1, At, B1); PG8_BAR; PG8_SCHED;
;             PG8_LDA(At, 0, 1); PG8_STAGE(PG8_SB(0, 0), b2, voffB); PG8_STAGE(PG8_SB(0, 1), b2 + hstep, voffB); PG8_STAGE(PG8_SA(0, 0), a2, voffA);
;             PG8_WAIT_V(8); PG8_WAIT_L(0); PG8_BAR; PG8_MMA(1, 0, At, B0); PG8_MMA(1, 1, At, B1); PG8_BAR; PG8_SCHED;
.LBB0_168:
	s_add_u32 s38, s64, 0xfffc0080
	s_addc_u32 s39, s65, -1
	s_add_i32 s47, 0, 0x10000
	s_cmp_eq_u32 s46, 12
	s_cselect_b32 vcc_hi, s31, s39
	s_cselect_b32 vcc_lo, s42, s38
	v_add_u32_e32 v138, s47, v141
	s_cselect_b32 s39, s29, s45
	s_cselect_b32 s38, s43, s44
	s_add_i32 s0, 0, 0x14000
	ds_read_b128 v[146:149], v138
	ds_read_b128 v[150:153], v138 offset:1024
	ds_read_b128 v[154:157], v138 offset:2048
	ds_read_b128 v[158:161], v138 offset:3072
	v_add_u32_e32 v138, s0, v141
	ds_read_b128 v[162:165], v138
	ds_read_b128 v[166:169], v138 offset:1024
	ds_read_b128 v[170:173], v138 offset:2048
	ds_read_b128 v[174:177], v138 offset:3072
	v_lshl_add_u64 v[138:139], s[64:65], 0, v[136:137]
	s_add_i32 m0, s85, 0xc000
	ds_read_b128 v[178:181], v144
	ds_read_b128 v[182:185], v144 offset:1024
	ds_read_b128 v[186:189], v144 offset:2048
	ds_read_b128 v[190:193], v144 offset:3072
	ds_read_b128 v[194:197], v144 offset:4096
	ds_read_b128 v[198:201], v144 offset:5120
	ds_read_b128 v[202:205], v144 offset:6144
	ds_read_b128 v[206:209], v144 offset:7168
	global_load_lds_dwordx4 v[138:139], off
	v_lshl_add_u64 v[138:139], s[64:65], 0, v[134:135]
	s_add_i32 m0, s85, 0xe000
	s_nop 0
	global_load_lds_dwordx4 v[138:139], off
	s_waitcnt vmcnt(8)
	s_waitcnt lgkmcnt(0)
	s_barrier
	s_waitcnt lgkmcnt(0)
	v_mfma_f32_16x16x32_bf16 v[124:127], v[146:149], v[178:181], v[124:127]
	v_mfma_f32_16x16x32_bf16 v[116:119], v[154:157], v[178:181], v[116:119]
	v_mfma_f32_16x16x32_bf16 v[108:111], v[146:149], v[186:189], v[108:111]
	v_mfma_f32_16x16x32_bf16 v[100:103], v[154:157], v[186:189], v[100:103]
	v_mfma_f32_16x16x32_bf16 v[92:95], v[146:149], v[194:197], v[92:95]
	v_mfma_f32_16x16x32_bf16 v[84:87], v[154:157], v[194:197], v[84:87]
	v_mfma_f32_16x16x32_bf16 v[76:79], v[146:149], v[202:205], v[76:79]
	v_mfma_f32_16x16x32_bf16 v[68:71], v[154:157], v[202:205], v[68:71]
	v_mfma_f32_16x16x32_bf16 v[124:127], v[150:153], v[182:185], v[124:127]
	v_mfma_f32_16x16x32_bf16 v[116:119], v[158:161], v[182:185], v[116:119]
	v_mfma_f32_16x16x32_bf16 v[108:111], v[150:153], v[190:193], v[108:111]
	v_mfma_f32_16x16x32_bf16 v[100:103], v[158:161], v[190:193], v[100:103]
	v_mfma_f32_16x16x32_bf16 v[92:95], v[150:153], v[198:201], v[92:95]
	v_mfma_f32_16x16x32_bf16 v[84:87], v[158:161], v[198:201], v[84:87]
	v_mfma_f32_16x16x32_bf16 v[76:79], v[150:153], v[206:209], v[76:79]
	v_mfma_f32_16x16x32_bf16 v[68:71], v[158:161], v[206:209], v[68:71]
	v_mfma_f32_16x16x32_bf16 v[120:123], v[162:165], v[178:181], v[120:123]
	v_mfma_f32_16x16x32_bf16 v[112:115], v[170:173], v[178:181], v[112:115]
	v_mfma_f32_16x16x32_bf16 v[104:107], v[162:165], v[186:189], v[104:107]
	v_mfma_f32_16x16x32_bf16 v[96:99], v[170:173], v[186:189], v[96:99]
	v_mfma_f32_16x16x32_bf16 v[88:91], v[162:165], v[194:197], v[88:91]
	v_mfma_f32_16x16x32_bf16 v[80:83], v[170:173], v[194:197], v[80:83]
	v_mfma_f32_16x16x32_bf16 v[72:75], v[162:165], v[202:205], v[72:75]
	v_mfma_f32_16x16x32_bf16 v[64:67], v[170:173], v[202:205], v[64:67]
	v_mfma_f32_16x16x32_bf16 v[120:123], v[166:169], v[182:185], v[120:123]
	v_mfma_f32_16x16x32_bf16 v[112:115], v[174:177], v[182:185], v[112:115]
	v_mfma_f32_16x16x32_bf16 v[104:107], v[166:169], v[190:193], v[104:107]
	v_mfma_f32_16x16x32_bf16 v[96:99], v[174:177], v[190:193], v[96:99]
	v_mfma_f32_16x16x32_bf16 v[88:91], v[166:169], v[198:201], v[88:91]
	v_mfma_f32_16x16x32_bf16 v[80:83], v[174:177], v[198:201], v[80:83]
	v_mfma_f32_16x16x32_bf16 v[72:75], v[166:169], v[206:209], v[72:75]
	v_mfma_f32_16x16x32_bf16 v[64:67], v[174:177], v[206:209], v[64:67]
	s_barrier
	s_add_i32 s1, s47, s63
	v_lshl_add_u64 v[138:139], s[38:39], 0, v[220:221]
	s_mov_b32 m0, s1
	ds_read_b128 v[178:181], v144 offset:16384
	ds_read_b128 v[182:185], v144 offset:17408
	ds_read_b128 v[186:189], v144 offset:18432
	ds_read_b128 v[190:193], v144 offset:19456
	ds_read_b128 v[194:197], v144 offset:20480
	ds_read_b128 v[198:201], v144 offset:21504
	ds_read_b128 v[202:205], v144 offset:22528
	ds_read_b128 v[206:209], v144 offset:23552
	global_load_lds_dwordx4 v[138:139], off
	s_add_i32 m0, s1, 0x2000
	s_add_u32 s68, s38, 0x40000
	v_lshl_add_u64 v[210:211], s[38:39], 0, v[128:129]
	s_addc_u32 s69, s39, 0
	s_add_i32 s0, s0, s63
	global_load_lds_dwordx4 v[210:211], off
	v_lshl_add_u64 v[212:213], s[68:69], 0, v[220:221]
	s_mov_b32 m0, s0
	v_lshl_add_u64 v[214:215], vcc, 0, v[130:131]
	global_load_lds_dwordx4 v[212:213], off
	v_lshl_add_u64 v[212:213], s[68:69], 0, v[128:129]
	s_add_i32 m0, s0, 0x2000
	s_nop 0
	global_load_lds_dwordx4 v[212:213], off
	v_lshl_add_u64 v[212:213], vcc, 0, v[132:133]
	s_mov_b32 m0, s85
	s_nop 0
	global_load_lds_dwordx4 v[212:213], off
	s_mov_b32 m0, s75
	s_nop 0
	global_load_lds_dwordx4 v[214:215], off
	s_waitcnt vmcnt(8)
	s_waitcnt lgkmcnt(0)
	s_barrier
; #define PG8_STAGE(bufoff, gbase, voff) do { _Pragma("unroll") for (int _i = 0; _i < 2; ++_i) \
;         __builtin_amdgcn_global_load_lds((const unsigned*)((const char*)(gbase) + (voff)[_i]), (PG8_LAS unsigned*)(lds + (bufoff) + ldsw + _i * 8192), 16, 0, 0); } while (0)
; #define PG8_LDA(dst, b, h) do { _Pragma("unroll") for (int m = 0; m < 4; ++m) _Pragma("unroll") for (int k = 0; k < 2; ++k) dst[m][k] = *(const PG8_LAS bf16x8*)(lds + PG8_SA(b, h) + aoff + m * 2048 + k * 1024); } while (0)
; #define PG8_LDB(dst, b, h) do { _Pragma("unroll") for (int n = 0; n < 2; ++n) _Pragma("unroll") for (int k = 0; k < 2; ++k) dst[n][k] = *(const PG8_LAS bf16x8*)(lds + PG8_SB(b, h) + boff + n * 2048 + k * 1024); } while (0)
; #define PG8_MMA(ai, bj, At, Bt) do { __builtin_amdgcn_s_setprio(1); _Pragma("unroll") for (int m = 0; m < 4; ++m) _Pragma("unroll") for (int n = 0; n < 2; ++n) _Pragma("unroll") for (int k = 0; k < 2; ++k) \
;         acc[ai][bj][m][n] = __builtin_amdgcn_mfma_f32_16x16x32_bf16(Bt[n][k], At[m][k], acc[ai][bj][m][n], 0, 0, 0); __builtin_amdgcn_s_setprio(0); } while (0)
; #define PG8_WAIT_V(n) asm volatile("s_waitcnt vmcnt(" #n ")" ::: "memory")
; #define PG8_WAIT_L(n) asm volatile("s_waitcnt lgkmcnt(" #n ")" ::: "memory")
; #define PG8_BAR __builtin_amdgcn_s_barrier()
; #define PG8_SCHED __builtin_amdgcn_sched_barrier(0)
; template <class Epi, class Sched, bool ALIGN_EPI = false, bool SP2 = false>
; __device__ __forceinline__ void gemm_phase(PG8_LAS unsigned char* lds, const Gemm g, const Sched& S, const Epi& E) {
;     ...
;             PG8_WAIT_V(8); PG8_WAIT_L(0); PG8_BAR; PG8_MMA(1, 0, At, B0); PG8_MMA(1, 1, At, B1); PG8_BAR; PG8_SCHED;
;             PG8_LDB(B0, 1, 0); PG8_LDB(B1, 1, 1); PG8_SCHED; PG8_LDA(At, 1, 0); PG8_STAGE(PG8_SA(0, 1), a2 + hstep, voffA);
;             PG8_WAIT_V(8); PG8_WAIT_L(0); PG8_BAR; PG8_MMA(0, 0, At, B0); PG8_MMA(0, 1, At, B1); PG8_BAR; PG8_SCHED;
	s_waitcnt lgkmcnt(0)
	v_mfma_f32_16x16x32_bf16 v[60:63], v[146:149], v[178:181], v[60:63]
	v_mfma_f32_16x16x32_bf16 v[52:55], v[154:157], v[178:181], v[52:55]
	v_mfma_f32_16x16x32_bf16 v[44:47], v[146:149], v[186:189], v[44:47]
	v_mfma_f32_16x16x32_bf16 v[36:39], v[154:157], v[186:189], v[36:39]
	v_mfma_f32_16x16x32_bf16 v[28:31], v[146:149], v[194:197], v[28:31]
	v_mfma_f32_16x16x32_bf16 v[20:23], v[154:157], v[194:197], v[20:23]
	v_mfma_f32_16x16x32_bf16 v[12:15], v[146:149], v[202:205], v[12:15]
	v_mfma_f32_16x16x32_bf16 v[4:7], v[154:157], v[202:205], v[4:7]
	v_mfma_f32_16x16x32_bf16 v[60:63], v[150:153], v[182:185], v[60:63]
	v_mfma_f32_16x16x32_bf16 v[52:55], v[158:161], v[182:185], v[52:55]
	v_mfma_f32_16x16x32_bf16 v[44:47], v[150:153], v[190:193], v[44:47]
	v_mfma_f32_16x16x32_bf16 v[36:39], v[158:161], v[190:193], v[36:39]
	v_mfma_f32_16x16x32_bf16 v[28:31], v[150:153], v[198:201], v[28:31]
	v_mfma_f32_16x16x32_bf16 v[20:23], v[158:161], v[198:201], v[20:23]
	v_mfma_f32_16x16x32_bf16 v[12:15], v[150:153], v[206:209], v[12:15]
	v_mfma_f32_16x16x32_bf16 v[4:7], v[158:161], v[206:209], v[4:7]
	v_mfma_f32_16x16x32_bf16 v[56:59], v[162:165], v[178:181], v[56:59]
	v_mfma_f32_16x16x32_bf16 v[48:51], v[170:173], v[178:181], v[48:51]
	v_mfma_f32_16x16x32_bf16 v[40:43], v[162:165], v[186:189], v[40:43]
	v_mfma_f32_16x16x32_bf16 v[32:35], v[170:173], v[186:189], v[32:35]
	v_mfma_f32_16x16x32_bf16 v[24:27], v[162:165], v[194:197], v[24:27]
	v_mfma_f32_16x16x32_bf16 v[16:19], v[170:173], v[194:197], v[16:19]
	v_mfma_f32_16x16x32_bf16 v[8:11], v[162:165], v[202:205], v[8:11]
	v_mfma_f32_16x16x32_bf16 v[0:3], v[170:173], v[202:205], v[0:3]
	v_mfma_f32_16x16x32_bf16 v[56:59], v[166:169], v[182:185], v[56:59]
	v_mfma_f32_16x16x32_bf16 v[48:51], v[174:177], v[182:185], v[48:51]
	v_mfma_f32_16x16x32_bf16 v[40:43], v[166:169], v[190:193], v[40:43]
	v_mfma_f32_16x16x32_bf16 v[32:35], v[174:177], v[190:193], v[32:35]
	v_mfma_f32_16x16x32_bf16 v[24:27], v[166:169], v[198:201], v[24:27]
	v_mfma_f32_16x16x32_bf16 v[16:19], v[174:177], v[198:201], v[16:19]
	v_mfma_f32_16x16x32_bf16 v[8:11], v[166:169], v[206:209], v[8:11]
	v_mfma_f32_16x16x32_bf16 v[0:3], v[174:177], v[206:209], v[0:3]
	s_barrier
	s_add_i32 s0, 0, 0x18000
	v_add_u32_e32 v145, s0, v141
	s_add_i32 s1, 0, 0x1c000
	ds_read_b128 v[146:149], v145
	ds_read_b128 v[150:153], v145 offset:1024
	ds_read_b128 v[154:157], v145 offset:2048
	ds_read_b128 v[158:161], v145 offset:3072
	v_add_u32_e32 v145, s1, v141
	ds_read_b128 v[162:165], v145
	ds_read_b128 v[166:169], v145 offset:1024
	ds_read_b128 v[170:173], v145 offset:2048
	ds_read_b128 v[174:177], v145 offset:3072
	s_add_u32 s68, vcc_lo, 0x40000
	s_addc_u32 s69, vcc_hi, 0
	s_mov_b32 m0, s76
	v_lshl_add_u64 v[216:217], s[68:69], 0, v[132:133]
	ds_read_b128 v[178:181], v144 offset:32768
	ds_read_b128 v[182:185], v144 offset:33792
	ds_read_b128 v[186:189], v144 offset:34816
	ds_read_b128 v[190:193], v144 offset:35840
	ds_read_b128 v[194:197], v144 offset:36864
	ds_read_b128 v[198:201], v144 offset:37888
	ds_read_b128 v[202:205], v144 offset:38912
	ds_read_b128 v[206:209], v144 offset:39936
	global_load_lds_dwordx4 v[216:217], off
	v_lshl_add_u64 v[216:217], s[68:69], 0, v[130:131]
	s_mov_b32 m0, s60
	s_nop 0
	global_load_lds_dwordx4 v[216:217], off
	s_waitcnt vmcnt(8)
	s_waitcnt lgkmcnt(0)
	s_barrier
	s_waitcnt lgkmcnt(0)
	v_mfma_f32_16x16x32_bf16 v[124:127], v[146:149], v[178:181], v[124:127]
	v_mfma_f32_16x16x32_bf16 v[116:119], v[154:157], v[178:181], v[116:119]
	v_mfma_f32_16x16x32_bf16 v[108:111], v[146:149], v[186:189], v[108:111]
	v_mfma_f32_16x16x32_bf16 v[100:103], v[154:157], v[186:189], v[100:103]
	v_mfma_f32_16x16x32_bf16 v[92:95], v[146:149], v[194:197], v[92:95]
	v_mfma_f32_16x16x32_bf16 v[84:87], v[154:157], v[194:197], v[84:87]
	v_mfma_f32_16x16x32_bf16 v[76:79], v[146:149], v[202:205], v[76:79]
	v_mfma_f32_16x16x32_bf16 v[68:71], v[154:157], v[202:205], v[68:71]
	v_mfma_f32_16x16x32_bf16 v[124:127], v[150:153], v[182:185], v[124:127]
	v_mfma_f32_16x16x32_bf16 v[116:119], v[158:161], v[182:185], v[116:119]
	v_mfma_f32_16x16x32_bf16 v[108:111], v[150:153], v[190:193], v[108:111]
	v_mfma_f32_16x16x32_bf16 v[100:103], v[158:161], v[190:193], v[100:103]
	v_mfma_f32_16x16x32_bf16 v[92:95], v[150:153], v[198:201], v[92:95]
	v_mfma_f32_16x16x32_bf16 v[84:87], v[158:161], v[198:201], v[84:87]
	v_mfma_f32_16x16x32_bf16 v[76:79], v[150:153], v[206:209], v[76:79]
	v_mfma_f32_16x16x32_bf16 v[68:71], v[158:161], v[206:209], v[68:71]
	v_mfma_f32_16x16x32_bf16 v[120:123], v[162:165], v[178:181], v[120:123]
	v_mfma_f32_16x16x32_bf16 v[112:115], v[170:173], v[178:181], v[112:115]
	v_mfma_f32_16x16x32_bf16 v[104:107], v[162:165], v[186:189], v[104:107]
	v_mfma_f32_16x16x32_bf16 v[96:99], v[170:173], v[186:189], v[96:99]
	v_mfma_f32_16x16x32_bf16 v[88:91], v[162:165], v[194:197], v[88:91]
	v_mfma_f32_16x16x32_bf16 v[80:83], v[170:173], v[194:197], v[80:83]
	v_mfma_f32_16x16x32_bf16 v[72:75], v[162:165], v[202:205], v[72:75]
	v_mfma_f32_16x16x32_bf16 v[64:67], v[170:173], v[202:205], v[64:67]
	v_mfma_f32_16x16x32_bf16 v[120:123], v[166:169], v[182:185], v[120:123]
	v_mfma_f32_16x16x32_bf16 v[112:115], v[174:177], v[182:185], v[112:115]
	v_mfma_f32_16x16x32_bf16 v[104:107], v[166:169], v[190:193], v[104:107]
	v_mfma_f32_16x16x32_bf16 v[96:99], v[174:177], v[190:193], v[96:99]
	v_mfma_f32_16x16x32_bf16 v[88:91], v[166:169], v[198:201], v[88:91]
	v_mfma_f32_16x16x32_bf16 v[80:83], v[174:177], v[198:201], v[80:83]
	v_mfma_f32_16x16x32_bf16 v[72:75], v[166:169], v[206:209], v[72:75]
	v_mfma_f32_16x16x32_bf16 v[64:67], v[174:177], v[206:209], v[64:67]
	s_barrier
; #define PG8_STAGE(bufoff, gbase, voff) do { _Pragma("unroll") for (int _i = 0; _i < 2; ++_i) \
;         __builtin_amdgcn_global_load_lds((const unsigned*)((const char*)(gbase) + (voff)[_i]), (PG8_LAS unsigned*)(lds + (bufoff) + ldsw + _i * 8192), 16, 0, 0); } while (0)
; #define PG8_LDA(dst, b, h) do { _Pragma("unroll") for (int m = 0; m < 4; ++m) _Pragma("unroll") for (int k = 0; k < 2; ++k) dst[m][k] = *(const PG8_LAS bf16x8*)(lds + PG8_SA(b, h) + aoff + m * 2048 + k * 1024); } while (0)
; #define PG8_MMA(ai, bj, At, Bt) do { __builtin_amdgcn_s_setprio(1); _Pragma("unroll") for (int m = 0; m < 4; ++m) _Pragma("unroll") for (int n = 0; n < 2; ++n) _Pragma("unroll") for (int k = 0; k < 2; ++k) \
;         acc[ai][bj][m][n] = __builtin_amdgcn_mfma_f32_16x16x32_bf16(Bt[n][k], At[m][k], acc[ai][bj][m][n], 0, 0, 0); __builtin_amdgcn_s_setprio(0); } while (0)
; #define PG8_WAIT_V(n) asm volatile("s_waitcnt vmcnt(" #n ")" ::: "memory")
; #define PG8_WAIT_L(n) asm volatile("s_waitcnt lgkmcnt(" #n ")" ::: "memory")
; #define PG8_BAR __builtin_amdgcn_s_barrier()
; #define PG8_SCHED __builtin_amdgcn_sched_barrier(0)
; template <class Epi, class Sched, bool ALIGN_EPI = false, bool SP2 = false>
; __device__ __forceinline__ void gemm_phase(PG8_LAS unsigned char* lds, const Gemm g, const Sched& S, const Epi& E) {
;     ...
;         for (int t = 0; t < nt; t += 2) {
;     ...
;             PG8_LDA(At, 1, 1); PG8_STAGE(PG8_SB(1, 0), b3, voffB); PG8_STAGE(PG8_SB(1, 1), b3 + hstep, voffB); PG8_STAGE(PG8_SA(1, 0), a3, voffA);
;             PG8_WAIT_V(8); PG8_WAIT_L(0); PG8_BAR; PG8_MMA(1, 0, At, B0); PG8_MMA(1, 1, At, B1); PG8_BAR; PG8_SCHED;
	s_add_i32 s0, s0, s63
	v_lshl_add_u64 v[138:139], v[138:139], 0, s[92:93]
	s_mov_b32 m0, s0
	ds_read_b128 v[178:181], v144 offset:49152
	ds_read_b128 v[182:185], v144 offset:50176
	ds_read_b128 v[186:189], v144 offset:51200
	ds_read_b128 v[190:193], v144 offset:52224
	ds_read_b128 v[194:197], v144 offset:53248
	ds_read_b128 v[198:201], v144 offset:54272
	ds_read_b128 v[202:205], v144 offset:55296
	ds_read_b128 v[206:209], v144 offset:56320
	global_load_lds_dwordx4 v[138:139], off
	s_add_i32 m0, s0, 0x2000
	s_add_u32 s38, s38, 0x40080
	v_lshl_add_u64 v[138:139], v[210:211], 0, s[92:93]
	s_addc_u32 s39, s39, 0
	s_add_i32 s0, s1, s63
	global_load_lds_dwordx4 v[138:139], off
	v_lshl_add_u64 v[138:139], s[38:39], 0, v[220:221]
	s_mov_b32 m0, s0
	s_nop 0
	global_load_lds_dwordx4 v[138:139], off
	v_lshl_add_u64 v[138:139], s[38:39], 0, v[128:129]
	s_add_i32 m0, s0, 0x2000
	s_nop 0
	global_load_lds_dwordx4 v[138:139], off
	v_lshl_add_u64 v[138:139], v[212:213], 0, s[92:93]
	s_mov_b32 m0, s50
	s_nop 0
	global_load_lds_dwordx4 v[138:139], off
	v_lshl_add_u64 v[138:139], v[214:215], 0, s[92:93]
	s_mov_b32 m0, s4
	s_nop 0
	global_load_lds_dwordx4 v[138:139], off
	s_waitcnt vmcnt(8)
	s_waitcnt lgkmcnt(0)
	s_barrier
	s_waitcnt lgkmcnt(0)
	v_mfma_f32_16x16x32_bf16 v[60:63], v[146:149], v[178:181], v[60:63]
	v_mfma_f32_16x16x32_bf16 v[52:55], v[154:157], v[178:181], v[52:55]
	v_mfma_f32_16x16x32_bf16 v[44:47], v[146:149], v[186:189], v[44:47]
	v_mfma_f32_16x16x32_bf16 v[36:39], v[154:157], v[186:189], v[36:39]
	v_mfma_f32_16x16x32_bf16 v[28:31], v[146:149], v[194:197], v[28:31]
	v_mfma_f32_16x16x32_bf16 v[20:23], v[154:157], v[194:197], v[20:23]
	v_mfma_f32_16x16x32_bf16 v[12:15], v[146:149], v[202:205], v[12:15]
	v_mfma_f32_16x16x32_bf16 v[4:7], v[154:157], v[202:205], v[4:7]
	v_mfma_f32_16x16x32_bf16 v[60:63], v[150:153], v[182:185], v[60:63]
	v_mfma_f32_16x16x32_bf16 v[52:55], v[158:161], v[182:185], v[52:55]
	v_mfma_f32_16x16x32_bf16 v[44:47], v[150:153], v[190:193], v[44:47]
	v_mfma_f32_16x16x32_bf16 v[36:39], v[158:161], v[190:193], v[36:39]
	v_mfma_f32_16x16x32_bf16 v[28:31], v[150:153], v[198:201], v[28:31]
	v_mfma_f32_16x16x32_bf16 v[20:23], v[158:161], v[198:201], v[20:23]
	v_mfma_f32_16x16x32_bf16 v[12:15], v[150:153], v[206:209], v[12:15]
	v_mfma_f32_16x16x32_bf16 v[4:7], v[158:161], v[206:209], v[4:7]
	v_mfma_f32_16x16x32_bf16 v[56:59], v[162:165], v[178:181], v[56:59]
	v_mfma_f32_16x16x32_bf16 v[48:51], v[170:173], v[178:181], v[48:51]
	v_mfma_f32_16x16x32_bf16 v[40:43], v[162:165], v[186:189], v[40:43]
	v_mfma_f32_16x16x32_bf16 v[32:35], v[170:173], v[186:189], v[32:35]
	v_mfma_f32_16x16x32_bf16 v[24:27], v[162:165], v[194:197], v[24:27]
	v_mfma_f32_16x16x32_bf16 v[16:19], v[170:173], v[194:197], v[16:19]
	v_mfma_f32_16x16x32_bf16 v[8:11], v[162:165], v[202:205], v[8:11]
	v_mfma_f32_16x16x32_bf16 v[0:3], v[170:173], v[202:205], v[0:3]
	v_mfma_f32_16x16x32_bf16 v[56:59], v[166:169], v[182:185], v[56:59]
	v_mfma_f32_16x16x32_bf16 v[48:51], v[174:177], v[182:185], v[48:51]
	v_mfma_f32_16x16x32_bf16 v[40:43], v[166:169], v[190:193], v[40:43]
	v_mfma_f32_16x16x32_bf16 v[32:35], v[174:177], v[190:193], v[32:35]
	v_mfma_f32_16x16x32_bf16 v[24:27], v[166:169], v[198:201], v[24:27]
	v_mfma_f32_16x16x32_bf16 v[16:19], v[174:177], v[198:201], v[16:19]
	v_mfma_f32_16x16x32_bf16 v[8:11], v[166:169], v[206:209], v[8:11]
	v_mfma_f32_16x16x32_bf16 v[0:3], v[174:177], v[206:209], v[0:3]
	s_barrier
	s_add_i32 s46, s46, 2
	s_add_u32 s44, s44, 0x100
	s_addc_u32 s45, s45, 0
	s_add_u32 s64, s64, 0x100
	s_addc_u32 s65, s65, 0
	s_cmp_gt_u32 s46, 13
	s_cbranch_scc0 .LBB0_168
	s_and_b64 vcc, exec, s[26:27]
	s_cbranch_vccz .LBB0_171
	s_barrier

; #define PG8_WAIT_V(n) asm volatile("s_waitcnt vmcnt(" #n ")" ::: "memory")
; #define PG8_BAR __builtin_amdgcn_s_barrier()
; template <class Epi, class Sched, bool ALIGN_EPI = false, bool SP2 = false>
; __device__ __forceinline__ void gemm_phase(PG8_LAS unsigned char* lds, const Gemm g, const Sched& S, const Epi& E) {
;     ...
;     PG8_WAIT_V(0);
;     if constexpr (!ALIGN_EPI) { if (wr == 0) PG8_BAR; }
;     PG8_BAR;
.LBB0_174:
	s_setprio 0
	s_waitcnt vmcnt(0)
	v_readlane_b32 s69, v255, 56
	v_readlane_b32 s89, v255, 57
	s_barrier
